# nt also on the GLU epilogue's y loads (last reader) and the final RMSNorm row loads
# baseline (speedup 1.0000x reference)
; __device__ __forceinline__ unsigned cvt_pk_bf16(float lo, float hi) { const f32x2 v = {lo, hi}; return __builtin_bit_cast(unsigned, __builtin_convertvector(v, bfx2_t)); }
; __device__ __forceinline__ float bflo(unsigned w) { return __uint_as_float(w << 16); }
; __device__ __forceinline__ float bfhi(unsigned w) { return __uint_as_float(w & 0xffff0000u); }
; __device__ __forceinline__ float fsigmoid(float x) { return __builtin_amdgcn_rcpf(1.0f + __builtin_amdgcn_exp2f(-1.4426950408889634f * x)); }
;     __device__ __forceinline__ void operator()(const AccT& acc, const Unit& u, int ui, int wr, int wc, int fr, int fq) const {
; #pragma unroll
;         for (int ai = 0; ai < 2; ++ai) {
;             u32x4 yv[4][2];
; #pragma unroll
;             for (int m = 0; m < 4; ++m)
; #pragma unroll
;                 for (int bj = 0; bj < 2; ++bj) yv[m][bj] = *GP(const u32x4, Y + (size_t)(u.pm * 256 + ai * 128 + wr * 64 + m * 16 + fr) * 512 + u.pn * 256 + bj * 128 + wc * 32 + 8 * fq);
; #pragma unroll
;             for (int m = 0; m < 4; ++m) {
;                 const int row = u.pm * 256 + ai * 128 + wr * 64 + m * 16 + fr;
; #pragma unroll
;                 for (int bj = 0; bj < 2; ++bj) {
;                     const int col = u.pn * 256 + bj * 128 + wc * 32 + 8 * fq;
;                     const u32x4 y = yv[m][bj];
;                     const f32x4 a0 = acc[ai][bj][m][0], a1 = acc[ai][bj][m][1];
;                     u32x4 w;
;                     w.x = cvt_pk_bf16(bflo(y.x) * fsigmoid(a0[0]), bfhi(y.x) * fsigmoid(a0[1]));
;                     w.y = cvt_pk_bf16(bflo(y.y) * fsigmoid(a0[2]), bfhi(y.y) * fsigmoid(a0[3]));
;                     w.z = cvt_pk_bf16(bflo(y.z) * fsigmoid(a1[0]), bfhi(y.z) * fsigmoid(a1[1]));
;                     w.w = cvt_pk_bf16(bflo(y.w) * fsigmoid(a1[2]), bfhi(y.w) * fsigmoid(a1[3]));
;                     *GP(u32x4, MIX + (size_t)row * DM + col) = w;
;                 }
;             }
.LBB0_299:
	v_lshl_add_u32 v194, s76, 8, v215
	s_lshl_b32 s12, s77, 8
	s_ashr_i32 s13, s12, 31
	v_ashrrev_i32_e32 v195, 31, v194
	v_lshl_add_u64 v[196:197], s[12:13], 1, v[192:193]
	v_lshlrev_b64 v[116:117], 10, v[194:195]
	v_lshl_add_u64 v[116:117], v[196:197], 0, v[116:117]
	global_load_dwordx4 v[156:159], v[116:117], off nt
	global_load_dwordx4 v[152:155], v[116:117], off offset:256 nt
	v_or_b32_e32 v202, 16, v194
	v_ashrrev_i32_e32 v203, 31, v202
	v_lshlrev_b64 v[116:117], 10, v[202:203]
	v_lshl_add_u64 v[116:117], v[196:197], 0, v[116:117]
	global_load_dwordx4 v[148:151], v[116:117], off nt
	global_load_dwordx4 v[144:147], v[116:117], off offset:256 nt
	v_mul_f32_e32 v140, 0xbfb8aa3b, v140
	v_mul_f32_e32 v141, 0xbfb8aa3b, v141
	v_exp_f32_e32 v140, v140
	v_exp_f32_e32 v141, v141
	v_mul_f32_e32 v132, 0xbfb8aa3b, v132
	v_mul_f32_e32 v133, 0xbfb8aa3b, v133
	v_add_f32_e32 v140, 1.0, v140
	v_add_f32_e32 v141, 1.0, v141
	v_rcp_f32_e32 v140, v140
	v_rcp_f32_e32 v141, v141
	v_exp_f32_e32 v132, v132
	v_exp_f32_e32 v133, v133
	v_mul_f32_e32 v120, 0xbfb8aa3b, v120
	v_mul_f32_e32 v121, 0xbfb8aa3b, v121
	v_add_f32_e32 v132, 1.0, v132
	v_add_f32_e32 v133, 1.0, v133
	v_rcp_f32_e32 v132, v132
	v_rcp_f32_e32 v133, v133
	v_exp_f32_e32 v120, v120
	v_exp_f32_e32 v121, v121
	v_or_b32_e32 v200, 32, v194
	v_ashrrev_i32_e32 v201, 31, v200
	v_or_b32_e32 v204, s12, v217
	v_lshlrev_b64 v[116:117], 10, v[200:201]
	v_or_b32_e32 v198, 48, v194
	v_add_f32_e32 v120, 1.0, v120
	v_add_f32_e32 v121, 1.0, v121
	v_lshl_add_u64 v[116:117], v[196:197], 0, v[116:117]
	v_ashrrev_i32_e32 v199, 31, v198
	v_lshlrev_b64 v[206:207], 11, v[194:195]
	v_ashrrev_i32_e32 v205, 31, v204
	v_rcp_f32_e32 v120, v120
	v_rcp_f32_e32 v121, v121
	global_load_dwordx4 v[136:139], v[116:117], off nt
	global_load_dwordx4 v[128:131], v[116:117], off offset:256 nt
	v_lshlrev_b64 v[116:117], 10, v[198:199]
	v_lshl_add_u64 v[116:117], v[196:197], 0, v[116:117]
	global_load_dwordx4 v[124:127], v[116:117], off nt
	s_nop 0
	global_load_dwordx4 v[116:119], v[116:117], off offset:256 nt
	v_mul_f32_e32 v112, 0xbfb8aa3b, v112
	v_mul_f32_e32 v113, 0xbfb8aa3b, v113
	v_exp_f32_e32 v112, v112
	v_exp_f32_e32 v113, v113
	v_mul_f32_e32 v108, 0xbfb8aa3b, v108
	v_mul_f32_e32 v109, 0xbfb8aa3b, v109
	v_add_f32_e32 v112, 1.0, v112
	v_add_f32_e32 v113, 1.0, v113
	v_rcp_f32_e32 v112, v112
	v_rcp_f32_e32 v113, v113
	v_exp_f32_e32 v108, v108
	v_exp_f32_e32 v109, v109
	v_mul_f32_e32 v104, 0xbfb8aa3b, v104
	v_mul_f32_e32 v105, 0xbfb8aa3b, v105
	v_add_f32_e32 v108, 1.0, v108
	v_add_f32_e32 v109, 1.0, v109
	v_rcp_f32_e32 v108, v108
	v_rcp_f32_e32 v109, v109
	v_exp_f32_e32 v104, v104
	v_exp_f32_e32 v105, v105
	v_mul_f32_e32 v100, 0xbfb8aa3b, v100
	v_mul_f32_e32 v101, 0xbfb8aa3b, v101
	v_add_f32_e32 v104, 1.0, v104
	v_add_f32_e32 v105, 1.0, v105
	v_rcp_f32_e32 v104, v104
	v_rcp_f32_e32 v105, v105
	v_exp_f32_e32 v100, v100
	v_exp_f32_e32 v101, v101
	v_mul_f32_e32 v96, 0xbfb8aa3b, v96
	v_mul_f32_e32 v97, 0xbfb8aa3b, v97
	v_add_f32_e32 v100, 1.0, v100
	v_add_f32_e32 v101, 1.0, v101
	v_rcp_f32_e32 v100, v100
	v_rcp_f32_e32 v101, v101
	v_exp_f32_e32 v96, v96
	v_exp_f32_e32 v97, v97
	s_waitcnt vmcnt(0)
	v_lshlrev_b32_e32 v218, 16, v156
	v_and_b32_e32 v219, 0xffff0000, v156
	v_pk_mul_f32 v[140:141], v[140:141], v[218:219]
	v_lshlrev_b32_e32 v156, 16, v157
	v_cvt_pk_bf16_f32 v140, v140, v141
	v_mul_f32_e32 v141, 0xbfb8aa3b, v142
	v_exp_f32_e32 v141, v141
	v_and_b32_e32 v157, 0xffff0000, v157
	v_add_f32_e32 v96, 1.0, v96
	v_add_f32_e32 v97, 1.0, v97
	v_add_f32_e32 v141, 1.0, v141
	v_rcp_f32_e32 v142, v141
	v_mul_f32_e32 v141, 0xbfb8aa3b, v143
	v_exp_f32_e32 v141, v141
	v_rcp_f32_e32 v96, v96
	v_rcp_f32_e32 v97, v97
	v_mul_f32_e32 v92, 0xbfb8aa3b, v92
	v_add_f32_e32 v141, 1.0, v141
	v_rcp_f32_e32 v143, v141
	v_mul_f32_e32 v93, 0xbfb8aa3b, v93
	v_exp_f32_e32 v92, v92
	v_exp_f32_e32 v93, v93
	v_pk_mul_f32 v[142:143], v[142:143], v[156:157]
	v_mul_f32_e32 v88, 0xbfb8aa3b, v88
	v_cvt_pk_bf16_f32 v141, v142, v143
	v_lshlrev_b32_e32 v142, 16, v158
	v_and_b32_e32 v143, 0xffff0000, v158
	v_pk_mul_f32 v[132:133], v[132:133], v[142:143]
	v_add_f32_e32 v92, 1.0, v92
	v_cvt_pk_bf16_f32 v142, v132, v133
	v_mul_f32_e32 v132, 0xbfb8aa3b, v134
	v_mul_f32_e32 v133, 0xbfb8aa3b, v135
	v_exp_f32_e32 v132, v132
	v_exp_f32_e32 v133, v133
	v_lshlrev_b32_e32 v134, 16, v159
	v_and_b32_e32 v135, 0xffff0000, v159
	v_add_f32_e32 v132, 1.0, v132
	v_add_f32_e32 v133, 1.0, v133
	v_rcp_f32_e32 v132, v132
	v_rcp_f32_e32 v133, v133
	v_add_f32_e32 v93, 1.0, v93
	v_rcp_f32_e32 v92, v92
	v_rcp_f32_e32 v93, v93
	v_pk_mul_f32 v[132:133], v[132:133], v[134:135]
	v_lshl_add_u64 v[134:135], s[18:19], 0, v[206:207]
	v_cvt_pk_bf16_f32 v143, v132, v133
	v_lshlrev_b64 v[132:133], 1, v[204:205]
	v_lshl_add_u64 v[134:135], v[134:135], 0, v[132:133]
	global_store_dwordx4 v[134:135], v[140:143], off
	v_mul_f32_e32 v89, 0xbfb8aa3b, v89
	v_exp_f32_e32 v88, v88
	v_lshlrev_b32_e32 v140, 16, v152
	v_and_b32_e32 v141, 0xffff0000, v152
	v_pk_mul_f32 v[120:121], v[120:121], v[140:141]
	v_lshlrev_b32_e32 v140, 16, v153
	v_cvt_pk_bf16_f32 v120, v120, v121
	v_mul_f32_e32 v121, 0xbfb8aa3b, v122
	v_exp_f32_e32 v121, v121
	v_and_b32_e32 v141, 0xffff0000, v153
	v_exp_f32_e32 v89, v89
	v_add_f32_e32 v88, 1.0, v88
	v_add_f32_e32 v121, 1.0, v121
	v_rcp_f32_e32 v122, v121
	v_mul_f32_e32 v121, 0xbfb8aa3b, v123
	v_exp_f32_e32 v121, v121
	v_add_f32_e32 v89, 1.0, v89
	v_rcp_f32_e32 v88, v88
	v_rcp_f32_e32 v89, v89
	v_add_f32_e32 v121, 1.0, v121
	v_rcp_f32_e32 v123, v121
	v_mul_f32_e32 v84, 0xbfb8aa3b, v84
	v_mul_f32_e32 v85, 0xbfb8aa3b, v85
	v_exp_f32_e32 v84, v84
	v_pk_mul_f32 v[122:123], v[122:123], v[140:141]
; __device__ __forceinline__ unsigned cvt_pk_bf16(float lo, float hi) { const f32x2 v = {lo, hi}; return __builtin_bit_cast(unsigned, __builtin_convertvector(v, bfx2_t)); }
; __device__ __forceinline__ float bflo(unsigned w) { return __uint_as_float(w << 16); }
; __device__ __forceinline__ float bfhi(unsigned w) { return __uint_as_float(w & 0xffff0000u); }
; __device__ __forceinline__ float fsigmoid(float x) { return __builtin_amdgcn_rcpf(1.0f + __builtin_amdgcn_exp2f(-1.4426950408889634f * x)); }
;     __device__ __forceinline__ void operator()(const AccT& acc, const Unit& u, int ui, int wr, int wc, int fr, int fq) const {
;     ...
;                     const f32x4 a0 = acc[ai][bj][m][0], a1 = acc[ai][bj][m][1];
;                     u32x4 w;
;                     w.x = cvt_pk_bf16(bflo(y.x) * fsigmoid(a0[0]), bfhi(y.x) * fsigmoid(a0[1]));
;                     w.y = cvt_pk_bf16(bflo(y.y) * fsigmoid(a0[2]), bfhi(y.y) * fsigmoid(a0[3]));
;                     w.z = cvt_pk_bf16(bflo(y.z) * fsigmoid(a1[0]), bfhi(y.z) * fsigmoid(a1[1]));
;                     w.w = cvt_pk_bf16(bflo(y.w) * fsigmoid(a1[2]), bfhi(y.w) * fsigmoid(a1[3]));
;                     *GP(u32x4, MIX + (size_t)row * DM + col) = w;
	v_exp_f32_e32 v85, v85
	v_cvt_pk_bf16_f32 v121, v122, v123
	v_lshlrev_b32_e32 v122, 16, v154
	v_and_b32_e32 v123, 0xffff0000, v154
	v_pk_mul_f32 v[112:113], v[112:113], v[122:123]
	v_add_f32_e32 v84, 1.0, v84
	v_cvt_pk_bf16_f32 v122, v112, v113
	v_mul_f32_e32 v112, 0xbfb8aa3b, v114
	v_mul_f32_e32 v113, 0xbfb8aa3b, v115
	v_exp_f32_e32 v112, v112
	v_exp_f32_e32 v113, v113
	v_lshlrev_b32_e32 v114, 16, v155
	v_and_b32_e32 v115, 0xffff0000, v155
	v_add_f32_e32 v112, 1.0, v112
	v_add_f32_e32 v113, 1.0, v113
	v_rcp_f32_e32 v112, v112
	v_rcp_f32_e32 v113, v113
	v_add_f32_e32 v85, 1.0, v85
	v_rcp_f32_e32 v84, v84
	v_rcp_f32_e32 v85, v85
	v_pk_mul_f32 v[112:113], v[112:113], v[114:115]
	v_lshlrev_b32_e32 v114, 16, v148
	v_and_b32_e32 v115, 0xffff0000, v148
	v_pk_mul_f32 v[108:109], v[108:109], v[114:115]
	v_lshlrev_b32_e32 v114, 16, v149
	v_cvt_pk_bf16_f32 v108, v108, v109
	v_mul_f32_e32 v109, 0xbfb8aa3b, v110
	v_exp_f32_e32 v109, v109
	v_and_b32_e32 v115, 0xffff0000, v149
	v_mul_f32_e32 v80, 0xbfb8aa3b, v80
	v_mul_f32_e32 v81, 0xbfb8aa3b, v81
	v_add_f32_e32 v109, 1.0, v109
	v_rcp_f32_e32 v110, v109
	v_mul_f32_e32 v109, 0xbfb8aa3b, v111
	v_exp_f32_e32 v109, v109
	v_exp_f32_e32 v80, v80
	v_exp_f32_e32 v81, v81
	v_mul_f32_e32 v76, 0xbfb8aa3b, v76
	v_add_f32_e32 v109, 1.0, v109
	v_rcp_f32_e32 v111, v109
	v_add_f32_e32 v80, 1.0, v80
	v_add_f32_e32 v81, 1.0, v81
	v_rcp_f32_e32 v80, v80
	v_pk_mul_f32 v[110:111], v[110:111], v[114:115]
	v_rcp_f32_e32 v81, v81
	v_cvt_pk_bf16_f32 v109, v110, v111
	v_lshlrev_b32_e32 v110, 16, v150
	v_and_b32_e32 v111, 0xffff0000, v150
	v_pk_mul_f32 v[104:105], v[104:105], v[110:111]
	v_mul_f32_e32 v77, 0xbfb8aa3b, v77
	v_cvt_pk_bf16_f32 v110, v104, v105
	v_mul_f32_e32 v104, 0xbfb8aa3b, v106
	v_mul_f32_e32 v105, 0xbfb8aa3b, v107
	v_exp_f32_e32 v104, v104
	v_exp_f32_e32 v105, v105
	v_lshlrev_b32_e32 v106, 16, v151
	v_and_b32_e32 v107, 0xffff0000, v151
	v_add_f32_e32 v104, 1.0, v104
	v_add_f32_e32 v105, 1.0, v105
	v_rcp_f32_e32 v104, v104
	v_rcp_f32_e32 v105, v105
	v_exp_f32_e32 v76, v76
	v_exp_f32_e32 v77, v77
	v_mul_f32_e32 v72, 0xbfb8aa3b, v72
	v_pk_mul_f32 v[104:105], v[104:105], v[106:107]
	v_lshlrev_b32_e32 v106, 16, v144
	v_and_b32_e32 v107, 0xffff0000, v144
	v_pk_mul_f32 v[100:101], v[100:101], v[106:107]
	v_lshlrev_b32_e32 v106, 16, v145
	v_cvt_pk_bf16_f32 v100, v100, v101
	v_mul_f32_e32 v101, 0xbfb8aa3b, v102
	v_exp_f32_e32 v101, v101
	v_and_b32_e32 v107, 0xffff0000, v145
	v_add_f32_e32 v76, 1.0, v76
	v_add_f32_e32 v77, 1.0, v77
	v_add_f32_e32 v101, 1.0, v101
	v_rcp_f32_e32 v102, v101
	v_mul_f32_e32 v101, 0xbfb8aa3b, v103
	v_exp_f32_e32 v101, v101
	v_rcp_f32_e32 v76, v76
	v_rcp_f32_e32 v77, v77
	v_mul_f32_e32 v73, 0xbfb8aa3b, v73
	v_add_f32_e32 v101, 1.0, v101
	v_rcp_f32_e32 v103, v101
	v_exp_f32_e32 v72, v72
	v_exp_f32_e32 v73, v73
	v_mul_f32_e32 v68, 0xbfb8aa3b, v68
	v_pk_mul_f32 v[102:103], v[102:103], v[106:107]
	v_add_f32_e32 v72, 1.0, v72
	v_cvt_pk_bf16_f32 v101, v102, v103
	v_lshlrev_b32_e32 v102, 16, v146
	v_and_b32_e32 v103, 0xffff0000, v146
	v_pk_mul_f32 v[96:97], v[96:97], v[102:103]
	v_add_f32_e32 v73, 1.0, v73
	v_cvt_pk_bf16_f32 v102, v96, v97
	v_mul_f32_e32 v96, 0xbfb8aa3b, v98
	v_mul_f32_e32 v97, 0xbfb8aa3b, v99
	v_exp_f32_e32 v96, v96
	v_exp_f32_e32 v97, v97
	v_lshlrev_b32_e32 v98, 16, v147
	v_and_b32_e32 v99, 0xffff0000, v147
	v_add_f32_e32 v96, 1.0, v96
	v_add_f32_e32 v97, 1.0, v97
	v_rcp_f32_e32 v96, v96
	v_rcp_f32_e32 v97, v97
	v_rcp_f32_e32 v72, v72
	v_rcp_f32_e32 v73, v73
	v_mul_f32_e32 v69, 0xbfb8aa3b, v69
	v_pk_mul_f32 v[96:97], v[96:97], v[98:99]
	v_lshlrev_b32_e32 v98, 16, v136
	v_and_b32_e32 v99, 0xffff0000, v136
	v_pk_mul_f32 v[92:93], v[92:93], v[98:99]
	v_lshlrev_b32_e32 v98, 16, v137
	v_cvt_pk_bf16_f32 v92, v92, v93
	v_mul_f32_e32 v93, 0xbfb8aa3b, v94
	v_exp_f32_e32 v93, v93
	v_and_b32_e32 v99, 0xffff0000, v137
	v_exp_f32_e32 v68, v68
	v_exp_f32_e32 v69, v69
	v_add_f32_e32 v93, 1.0, v93
	v_rcp_f32_e32 v94, v93
	v_mul_f32_e32 v93, 0xbfb8aa3b, v95
	v_exp_f32_e32 v93, v93
	v_add_f32_e32 v68, 1.0, v68
	v_add_f32_e32 v69, 1.0, v69
	v_rcp_f32_e32 v68, v68
	v_add_f32_e32 v93, 1.0, v93
	v_rcp_f32_e32 v95, v93
	v_rcp_f32_e32 v69, v69
	v_mul_f32_e32 v64, 0xbfb8aa3b, v64
	v_mul_f32_e32 v65, 0xbfb8aa3b, v65
	v_pk_mul_f32 v[94:95], v[94:95], v[98:99]
	v_exp_f32_e32 v64, v64
	v_cvt_pk_bf16_f32 v93, v94, v95
	v_lshlrev_b32_e32 v94, 16, v138
	v_and_b32_e32 v95, 0xffff0000, v138
	v_pk_mul_f32 v[88:89], v[88:89], v[94:95]
	v_exp_f32_e32 v65, v65
	v_cvt_pk_bf16_f32 v94, v88, v89
	v_mul_f32_e32 v88, 0xbfb8aa3b, v90
	v_mul_f32_e32 v89, 0xbfb8aa3b, v91
	v_exp_f32_e32 v88, v88
	v_exp_f32_e32 v89, v89
	v_lshlrev_b32_e32 v90, 16, v139
	v_and_b32_e32 v91, 0xffff0000, v139
	v_add_f32_e32 v88, 1.0, v88
	v_add_f32_e32 v89, 1.0, v89
	v_rcp_f32_e32 v88, v88
	v_rcp_f32_e32 v89, v89
	v_add_f32_e32 v64, 1.0, v64
	v_add_f32_e32 v65, 1.0, v65
	v_rcp_f32_e32 v64, v64
	v_pk_mul_f32 v[88:89], v[88:89], v[90:91]
	v_lshlrev_b32_e32 v90, 16, v128
	v_and_b32_e32 v91, 0xffff0000, v128
	v_pk_mul_f32 v[84:85], v[84:85], v[90:91]
	v_lshlrev_b32_e32 v90, 16, v129
	v_cvt_pk_bf16_f32 v84, v84, v85
	v_mul_f32_e32 v85, 0xbfb8aa3b, v86
	v_exp_f32_e32 v85, v85
	v_and_b32_e32 v91, 0xffff0000, v129
	v_rcp_f32_e32 v65, v65
	v_cvt_pk_bf16_f32 v123, v112, v113
	v_add_f32_e32 v85, 1.0, v85
	v_rcp_f32_e32 v86, v85
	v_mul_f32_e32 v85, 0xbfb8aa3b, v87
	v_exp_f32_e32 v85, v85
	v_lshlrev_b64 v[112:113], 11, v[202:203]
	v_cvt_pk_bf16_f32 v111, v104, v105
	v_lshl_add_u64 v[104:105], s[18:19], 0, v[112:113]
	v_add_f32_e32 v85, 1.0, v85
	v_rcp_f32_e32 v87, v85
	v_lshl_add_u64 v[104:105], v[104:105], 0, v[132:133]
	v_cvt_pk_bf16_f32 v103, v96, v97
; __device__ __forceinline__ unsigned cvt_pk_bf16(float lo, float hi) { const f32x2 v = {lo, hi}; return __builtin_bit_cast(unsigned, __builtin_convertvector(v, bfx2_t)); }
; __device__ __forceinline__ float bflo(unsigned w) { return __uint_as_float(w << 16); }
; __device__ __forceinline__ float bfhi(unsigned w) { return __uint_as_float(w & 0xffff0000u); }
; __device__ __forceinline__ float fsigmoid(float x) { return __builtin_amdgcn_rcpf(1.0f + __builtin_amdgcn_exp2f(-1.4426950408889634f * x)); }
;     __device__ __forceinline__ void operator()(const AccT& acc, const Unit& u, int ui, int wr, int wc, int fr, int fq) const {
;     ...
;             for (int m = 0; m < 4; ++m)
; #pragma unroll
;                 for (int bj = 0; bj < 2; ++bj) yv[m][bj] = *GP(const u32x4, Y + (size_t)(u.pm * 256 + ai * 128 + wr * 64 + m * 16 + fr) * 512 + u.pn * 256 + bj * 128 + wc * 32 + 8 * fq);
; #pragma unroll
;             for (int m = 0; m < 4; ++m) {
;                 const int row = u.pm * 256 + ai * 128 + wr * 64 + m * 16 + fr;
; #pragma unroll
;                 for (int bj = 0; bj < 2; ++bj) {
;                     const int col = u.pn * 256 + bj * 128 + wc * 32 + 8 * fq;
;                     const u32x4 y = yv[m][bj];
;                     const f32x4 a0 = acc[ai][bj][m][0], a1 = acc[ai][bj][m][1];
;                     u32x4 w;
;                     w.x = cvt_pk_bf16(bflo(y.x) * fsigmoid(a0[0]), bfhi(y.x) * fsigmoid(a0[1]));
;                     w.y = cvt_pk_bf16(bflo(y.y) * fsigmoid(a0[2]), bfhi(y.y) * fsigmoid(a0[3]));
;                     w.z = cvt_pk_bf16(bflo(y.z) * fsigmoid(a1[0]), bfhi(y.z) * fsigmoid(a1[1]));
;                     w.w = cvt_pk_bf16(bflo(y.w) * fsigmoid(a1[2]), bfhi(y.w) * fsigmoid(a1[3]));
;                     *GP(u32x4, MIX + (size_t)row * DM + col) = w;
;                 }
	v_lshlrev_b64 v[96:97], 11, v[200:201]
	v_pk_mul_f32 v[86:87], v[86:87], v[90:91]
	global_store_dwordx4 v[104:105], v[100:103], off offset:256
	v_cvt_pk_bf16_f32 v85, v86, v87
	v_lshlrev_b32_e32 v86, 16, v130
	v_and_b32_e32 v87, 0xffff0000, v130
	v_pk_mul_f32 v[80:81], v[80:81], v[86:87]
	v_cvt_pk_bf16_f32 v95, v88, v89
	v_cvt_pk_bf16_f32 v86, v80, v81
	v_mul_f32_e32 v80, 0xbfb8aa3b, v82
	v_mul_f32_e32 v81, 0xbfb8aa3b, v83
	v_exp_f32_e32 v80, v80
	v_exp_f32_e32 v81, v81
	v_lshlrev_b32_e32 v82, 16, v131
	v_and_b32_e32 v83, 0xffff0000, v131
	v_add_f32_e32 v80, 1.0, v80
	v_add_f32_e32 v81, 1.0, v81
	v_rcp_f32_e32 v80, v80
	v_rcp_f32_e32 v81, v81
	v_lshl_add_u64 v[88:89], s[18:19], 0, v[96:97]
	v_add_u32_e32 v102, 0x80, v194
	v_lshl_add_u64 v[88:89], v[88:89], 0, v[132:133]
	v_pk_mul_f32 v[80:81], v[80:81], v[82:83]
	v_lshlrev_b32_e32 v82, 16, v124
	v_and_b32_e32 v83, 0xffff0000, v124
	v_pk_mul_f32 v[76:77], v[76:77], v[82:83]
	v_lshlrev_b32_e32 v82, 16, v125
	v_cvt_pk_bf16_f32 v76, v76, v77
	v_mul_f32_e32 v77, 0xbfb8aa3b, v78
	v_exp_f32_e32 v77, v77
	v_and_b32_e32 v83, 0xffff0000, v125
	v_cvt_pk_bf16_f32 v87, v80, v81
	v_lshlrev_b64 v[80:81], 11, v[198:199]
	v_add_f32_e32 v77, 1.0, v77
	v_rcp_f32_e32 v78, v77
	v_mul_f32_e32 v77, 0xbfb8aa3b, v79
	v_exp_f32_e32 v77, v77
	v_ashrrev_i32_e32 v103, 31, v102
	global_store_dwordx4 v[134:135], v[120:123], off offset:256
	global_store_dwordx4 v[104:105], v[108:111], off
	v_add_f32_e32 v77, 1.0, v77
	v_rcp_f32_e32 v79, v77
	global_store_dwordx4 v[88:89], v[92:95], off
	global_store_dwordx4 v[88:89], v[84:87], off offset:256
	v_add_u32_e32 v96, 0x90, v194
	v_pk_mul_f32 v[78:79], v[78:79], v[82:83]
	v_ashrrev_i32_e32 v97, 31, v96
	v_cvt_pk_bf16_f32 v77, v78, v79
	v_lshlrev_b32_e32 v78, 16, v126
	v_and_b32_e32 v79, 0xffff0000, v126
	v_pk_mul_f32 v[72:73], v[72:73], v[78:79]
	v_mul_f32_e32 v60, 0xbfb8aa3b, v60
	v_cvt_pk_bf16_f32 v78, v72, v73
	v_mul_f32_e32 v72, 0xbfb8aa3b, v74
	v_mul_f32_e32 v73, 0xbfb8aa3b, v75
	v_exp_f32_e32 v72, v72
	v_exp_f32_e32 v73, v73
	v_lshlrev_b32_e32 v74, 16, v127
	v_and_b32_e32 v75, 0xffff0000, v127
	v_add_f32_e32 v72, 1.0, v72
	v_add_f32_e32 v73, 1.0, v73
	v_rcp_f32_e32 v72, v72
	v_rcp_f32_e32 v73, v73
	v_mul_f32_e32 v61, 0xbfb8aa3b, v61
	v_exp_f32_e32 v60, v60
	v_exp_f32_e32 v61, v61
	v_pk_mul_f32 v[72:73], v[72:73], v[74:75]
	v_lshlrev_b32_e32 v74, 16, v116
	v_and_b32_e32 v75, 0xffff0000, v116
	v_pk_mul_f32 v[68:69], v[68:69], v[74:75]
	v_lshlrev_b32_e32 v74, 16, v117
	v_cvt_pk_bf16_f32 v68, v68, v69
	v_mul_f32_e32 v69, 0xbfb8aa3b, v70
	v_exp_f32_e32 v69, v69
	v_and_b32_e32 v75, 0xffff0000, v117
	v_cvt_pk_bf16_f32 v79, v72, v73
	v_lshl_add_u64 v[72:73], s[18:19], 0, v[80:81]
	v_add_f32_e32 v69, 1.0, v69
	v_rcp_f32_e32 v70, v69
	v_mul_f32_e32 v69, 0xbfb8aa3b, v71
	v_exp_f32_e32 v69, v69
	v_lshl_add_u64 v[72:73], v[72:73], 0, v[132:133]
	global_store_dwordx4 v[72:73], v[76:79], off
	v_add_f32_e32 v60, 1.0, v60
	v_add_f32_e32 v69, 1.0, v69
	v_rcp_f32_e32 v71, v69
	v_add_f32_e32 v61, 1.0, v61
	v_rcp_f32_e32 v60, v60
	v_rcp_f32_e32 v61, v61
	v_pk_mul_f32 v[70:71], v[70:71], v[74:75]
	v_mul_f32_e32 v56, 0xbfb8aa3b, v56
	v_cvt_pk_bf16_f32 v69, v70, v71
	v_lshlrev_b32_e32 v70, 16, v118
	v_and_b32_e32 v71, 0xffff0000, v118
	v_pk_mul_f32 v[64:65], v[64:65], v[70:71]
	v_mul_f32_e32 v57, 0xbfb8aa3b, v57
	v_cvt_pk_bf16_f32 v70, v64, v65
	v_mul_f32_e32 v64, 0xbfb8aa3b, v66
	v_mul_f32_e32 v65, 0xbfb8aa3b, v67
	v_exp_f32_e32 v64, v64
	v_exp_f32_e32 v65, v65
	v_lshlrev_b32_e32 v66, 16, v119
	v_and_b32_e32 v67, 0xffff0000, v119
	v_add_f32_e32 v64, 1.0, v64
	v_add_f32_e32 v65, 1.0, v65
	v_rcp_f32_e32 v64, v64
	v_rcp_f32_e32 v65, v65
	v_exp_f32_e32 v56, v56
	v_exp_f32_e32 v57, v57
	v_mul_f32_e32 v52, 0xbfb8aa3b, v52
	v_pk_mul_f32 v[64:65], v[64:65], v[66:67]
	v_add_f32_e32 v56, 1.0, v56
	v_cvt_pk_bf16_f32 v71, v64, v65
	global_store_dwordx4 v[72:73], v[68:71], off offset:256
	v_lshlrev_b64 v[64:65], 10, v[102:103]
	v_lshl_add_u64 v[64:65], v[196:197], 0, v[64:65]
	global_load_dwordx4 v[98:101], v[64:65], off nt
	global_load_dwordx4 v[88:91], v[64:65], off offset:256 nt
	v_lshlrev_b64 v[64:65], 10, v[96:97]
	v_lshl_add_u64 v[64:65], v[196:197], 0, v[64:65]
	global_load_dwordx4 v[84:87], v[64:65], off nt
	global_load_dwordx4 v[80:83], v[64:65], off offset:256 nt
	v_add_f32_e32 v57, 1.0, v57
	v_rcp_f32_e32 v56, v56
	v_rcp_f32_e32 v57, v57
	v_mul_f32_e32 v53, 0xbfb8aa3b, v53
	v_exp_f32_e32 v52, v52
	v_exp_f32_e32 v53, v53
	v_add_u32_e32 v94, 0xa0, v194
	v_mul_f32_e32 v48, 0xbfb8aa3b, v48
	v_add_f32_e32 v52, 1.0, v52
	v_add_f32_e32 v53, 1.0, v53
	v_rcp_f32_e32 v52, v52
	v_rcp_f32_e32 v53, v53
	v_mul_f32_e32 v49, 0xbfb8aa3b, v49
	v_ashrrev_i32_e32 v95, 31, v94
	v_exp_f32_e32 v48, v48
	v_exp_f32_e32 v49, v49
	v_lshlrev_b64 v[64:65], 10, v[94:95]
	v_lshl_add_u64 v[64:65], v[196:197], 0, v[64:65]
	global_load_dwordx4 v[76:79], v[64:65], off nt
	global_load_dwordx4 v[72:75], v[64:65], off offset:256 nt
	v_add_f32_e32 v48, 1.0, v48
	v_add_f32_e32 v49, 1.0, v49
	v_rcp_f32_e32 v48, v48
	v_rcp_f32_e32 v49, v49
	v_mul_f32_e32 v44, 0xbfb8aa3b, v44
	v_mul_f32_e32 v45, 0xbfb8aa3b, v45
	v_exp_f32_e32 v44, v44
	v_exp_f32_e32 v45, v45
	v_mul_f32_e32 v40, 0xbfb8aa3b, v40
	v_mul_f32_e32 v41, 0xbfb8aa3b, v41
	v_add_f32_e32 v44, 1.0, v44
	v_add_f32_e32 v45, 1.0, v45
	v_rcp_f32_e32 v44, v44
	v_rcp_f32_e32 v45, v45
	v_exp_f32_e32 v40, v40
	v_exp_f32_e32 v41, v41
	v_mul_f32_e32 v36, 0xbfb8aa3b, v36
	v_mul_f32_e32 v37, 0xbfb8aa3b, v37
	v_add_f32_e32 v40, 1.0, v40
	v_add_f32_e32 v41, 1.0, v41
	v_rcp_f32_e32 v40, v40
	v_rcp_f32_e32 v41, v41
	v_exp_f32_e32 v36, v36
	v_exp_f32_e32 v37, v37
	v_add_u32_e32 v92, 0xb0, v194
	v_mul_f32_e32 v32, 0xbfb8aa3b, v32
	v_add_f32_e32 v36, 1.0, v36
	v_add_f32_e32 v37, 1.0, v37
	v_rcp_f32_e32 v36, v36
	v_rcp_f32_e32 v37, v37
	v_mul_f32_e32 v33, 0xbfb8aa3b, v33
	v_ashrrev_i32_e32 v93, 31, v92
	v_exp_f32_e32 v32, v32
	v_exp_f32_e32 v33, v33
	v_lshlrev_b64 v[64:65], 10, v[92:93]
	v_lshl_add_u64 v[64:65], v[196:197], 0, v[64:65]
	global_load_dwordx4 v[68:71], v[64:65], off nt
	s_nop 0
	global_load_dwordx4 v[64:67], v[64:65], off offset:256 nt
	v_add_f32_e32 v32, 1.0, v32
	v_add_f32_e32 v33, 1.0, v33
	v_rcp_f32_e32 v32, v32
	v_rcp_f32_e32 v33, v33
	v_mul_f32_e32 v28, 0xbfb8aa3b, v28
	v_mul_f32_e32 v29, 0xbfb8aa3b, v29
	v_exp_f32_e32 v28, v28
	v_exp_f32_e32 v29, v29
	v_mul_f32_e32 v24, 0xbfb8aa3b, v24
	v_mul_f32_e32 v25, 0xbfb8aa3b, v25
	v_add_f32_e32 v28, 1.0, v28
	v_add_f32_e32 v29, 1.0, v29
	v_rcp_f32_e32 v28, v28
	v_rcp_f32_e32 v29, v29
	v_exp_f32_e32 v24, v24
	v_exp_f32_e32 v25, v25
	v_mul_f32_e32 v20, 0xbfb8aa3b, v20
	v_mul_f32_e32 v21, 0xbfb8aa3b, v21
	v_add_f32_e32 v24, 1.0, v24
	s_waitcnt vmcnt(0)
; __device__ __forceinline__ unsigned cvt_pk_bf16(float lo, float hi) { const f32x2 v = {lo, hi}; return __builtin_bit_cast(unsigned, __builtin_convertvector(v, bfx2_t)); }
; __device__ __forceinline__ float bflo(unsigned w) { return __uint_as_float(w << 16); }
; __device__ __forceinline__ float bfhi(unsigned w) { return __uint_as_float(w & 0xffff0000u); }
; __device__ __forceinline__ float fsigmoid(float x) { return __builtin_amdgcn_rcpf(1.0f + __builtin_amdgcn_exp2f(-1.4426950408889634f * x)); }
;     __device__ __forceinline__ void operator()(const AccT& acc, const Unit& u, int ui, int wr, int wc, int fr, int fq) const {
;     ...
;             for (int m = 0; m < 4; ++m) {
;                 const int row = u.pm * 256 + ai * 128 + wr * 64 + m * 16 + fr;
; #pragma unroll
;                 for (int bj = 0; bj < 2; ++bj) {
;                     const int col = u.pn * 256 + bj * 128 + wc * 32 + 8 * fq;
;                     const u32x4 y = yv[m][bj];
;                     const f32x4 a0 = acc[ai][bj][m][0], a1 = acc[ai][bj][m][1];
;                     u32x4 w;
;                     w.x = cvt_pk_bf16(bflo(y.x) * fsigmoid(a0[0]), bfhi(y.x) * fsigmoid(a0[1]));
;                     w.y = cvt_pk_bf16(bflo(y.y) * fsigmoid(a0[2]), bfhi(y.y) * fsigmoid(a0[3]));
;                     w.z = cvt_pk_bf16(bflo(y.z) * fsigmoid(a1[0]), bfhi(y.z) * fsigmoid(a1[1]));
;                     w.w = cvt_pk_bf16(bflo(y.w) * fsigmoid(a1[2]), bfhi(y.w) * fsigmoid(a1[3]));
;                     *GP(u32x4, MIX + (size_t)row * DM + col) = w;
	v_lshlrev_b32_e32 v104, 16, v98
	v_and_b32_e32 v105, 0xffff0000, v98
	v_pk_mul_f32 v[60:61], v[60:61], v[104:105]
	v_lshlrev_b32_e32 v98, 16, v99
	v_cvt_pk_bf16_f32 v60, v60, v61
	v_mul_f32_e32 v61, 0xbfb8aa3b, v62
	v_exp_f32_e32 v61, v61
	v_and_b32_e32 v99, 0xffff0000, v99
	v_add_f32_e32 v25, 1.0, v25
	v_rcp_f32_e32 v24, v24
	v_add_f32_e32 v61, 1.0, v61
	v_rcp_f32_e32 v62, v61
	v_mul_f32_e32 v61, 0xbfb8aa3b, v63
	v_exp_f32_e32 v61, v61
	v_rcp_f32_e32 v25, v25
	v_exp_f32_e32 v20, v20
	v_exp_f32_e32 v21, v21
	v_add_f32_e32 v61, 1.0, v61
	v_rcp_f32_e32 v63, v61
	v_add_f32_e32 v20, 1.0, v20
	v_add_f32_e32 v21, 1.0, v21
	v_rcp_f32_e32 v20, v20
	v_pk_mul_f32 v[62:63], v[62:63], v[98:99]
	v_rcp_f32_e32 v21, v21
	v_cvt_pk_bf16_f32 v61, v62, v63
	v_lshlrev_b32_e32 v62, 16, v100
	v_and_b32_e32 v63, 0xffff0000, v100
	v_pk_mul_f32 v[56:57], v[56:57], v[62:63]
	v_mul_f32_e32 v16, 0xbfb8aa3b, v16
	v_cvt_pk_bf16_f32 v62, v56, v57
	v_mul_f32_e32 v56, 0xbfb8aa3b, v58
	v_mul_f32_e32 v57, 0xbfb8aa3b, v59
	v_exp_f32_e32 v56, v56
	v_exp_f32_e32 v57, v57
	v_lshlrev_b32_e32 v58, 16, v101
	v_and_b32_e32 v59, 0xffff0000, v101
	v_add_f32_e32 v56, 1.0, v56
	v_add_f32_e32 v57, 1.0, v57
	v_rcp_f32_e32 v56, v56
	v_rcp_f32_e32 v57, v57
	v_mul_f32_e32 v17, 0xbfb8aa3b, v17
	v_exp_f32_e32 v16, v16
	v_exp_f32_e32 v17, v17
	v_pk_mul_f32 v[56:57], v[56:57], v[58:59]
	v_lshlrev_b32_e32 v58, 16, v88
	v_and_b32_e32 v59, 0xffff0000, v88
	v_pk_mul_f32 v[52:53], v[52:53], v[58:59]
	v_lshlrev_b32_e32 v58, 16, v89
	v_cvt_pk_bf16_f32 v52, v52, v53
	v_mul_f32_e32 v53, 0xbfb8aa3b, v54
	v_exp_f32_e32 v53, v53
	v_and_b32_e32 v59, 0xffff0000, v89
	v_add_f32_e32 v16, 1.0, v16
	v_add_f32_e32 v17, 1.0, v17
	v_add_f32_e32 v53, 1.0, v53
	v_rcp_f32_e32 v54, v53
	v_mul_f32_e32 v53, 0xbfb8aa3b, v55
	v_exp_f32_e32 v53, v53
	v_rcp_f32_e32 v16, v16
	v_rcp_f32_e32 v17, v17
	v_mul_f32_e32 v12, 0xbfb8aa3b, v12
	v_add_f32_e32 v53, 1.0, v53
	v_rcp_f32_e32 v55, v53
	v_mul_f32_e32 v13, 0xbfb8aa3b, v13
	v_exp_f32_e32 v12, v12
	v_exp_f32_e32 v13, v13
	v_pk_mul_f32 v[54:55], v[54:55], v[58:59]
	v_mul_f32_e32 v8, 0xbfb8aa3b, v8
	v_cvt_pk_bf16_f32 v53, v54, v55
	v_lshlrev_b32_e32 v54, 16, v90
	v_and_b32_e32 v55, 0xffff0000, v90
	v_pk_mul_f32 v[48:49], v[48:49], v[54:55]
	v_add_f32_e32 v12, 1.0, v12
	v_cvt_pk_bf16_f32 v54, v48, v49
	v_mul_f32_e32 v48, 0xbfb8aa3b, v50
	v_mul_f32_e32 v49, 0xbfb8aa3b, v51
	v_exp_f32_e32 v48, v48
	v_exp_f32_e32 v49, v49
	v_lshlrev_b32_e32 v50, 16, v91
	v_and_b32_e32 v51, 0xffff0000, v91
	v_add_f32_e32 v48, 1.0, v48
	v_add_f32_e32 v49, 1.0, v49
	v_rcp_f32_e32 v48, v48
	v_rcp_f32_e32 v49, v49
	v_add_f32_e32 v13, 1.0, v13
	v_rcp_f32_e32 v12, v12
	v_rcp_f32_e32 v13, v13
	v_pk_mul_f32 v[48:49], v[48:49], v[50:51]
	v_lshlrev_b32_e32 v50, 16, v84
	v_and_b32_e32 v51, 0xffff0000, v84
	v_pk_mul_f32 v[44:45], v[44:45], v[50:51]
	v_lshlrev_b32_e32 v50, 16, v85
	v_cvt_pk_bf16_f32 v44, v44, v45
	v_mul_f32_e32 v45, 0xbfb8aa3b, v46
	v_exp_f32_e32 v45, v45
	v_and_b32_e32 v51, 0xffff0000, v85
	v_mul_f32_e32 v9, 0xbfb8aa3b, v9
	v_exp_f32_e32 v8, v8
	v_add_f32_e32 v45, 1.0, v45
	v_rcp_f32_e32 v46, v45
	v_mul_f32_e32 v45, 0xbfb8aa3b, v47
	v_exp_f32_e32 v45, v45
	v_exp_f32_e32 v9, v9
	v_add_f32_e32 v8, 1.0, v8
	v_rcp_f32_e32 v8, v8
	v_add_f32_e32 v45, 1.0, v45
	v_rcp_f32_e32 v47, v45
	v_add_f32_e32 v9, 1.0, v9
	v_rcp_f32_e32 v9, v9
	v_mul_f32_e32 v4, 0xbfb8aa3b, v4
	v_pk_mul_f32 v[46:47], v[46:47], v[50:51]
	v_mul_f32_e32 v5, 0xbfb8aa3b, v5
	v_cvt_pk_bf16_f32 v45, v46, v47
	v_lshlrev_b32_e32 v46, 16, v86
	v_and_b32_e32 v47, 0xffff0000, v86
	v_pk_mul_f32 v[40:41], v[40:41], v[46:47]
	v_exp_f32_e32 v4, v4
	v_cvt_pk_bf16_f32 v46, v40, v41
	v_mul_f32_e32 v40, 0xbfb8aa3b, v42
	v_mul_f32_e32 v41, 0xbfb8aa3b, v43
	v_exp_f32_e32 v40, v40
	v_exp_f32_e32 v41, v41
	v_lshlrev_b32_e32 v42, 16, v87
	v_and_b32_e32 v43, 0xffff0000, v87
	v_add_f32_e32 v40, 1.0, v40
	v_add_f32_e32 v41, 1.0, v41
	v_rcp_f32_e32 v40, v40
	v_rcp_f32_e32 v41, v41
	v_exp_f32_e32 v5, v5
	v_add_f32_e32 v4, 1.0, v4
	v_rcp_f32_e32 v4, v4
	v_pk_mul_f32 v[40:41], v[40:41], v[42:43]
	v_lshlrev_b32_e32 v42, 16, v80
	v_and_b32_e32 v43, 0xffff0000, v80
	v_pk_mul_f32 v[36:37], v[36:37], v[42:43]
	v_lshlrev_b32_e32 v42, 16, v81
	v_cvt_pk_bf16_f32 v36, v36, v37
	v_mul_f32_e32 v37, 0xbfb8aa3b, v38
	v_exp_f32_e32 v37, v37
	v_and_b32_e32 v43, 0xffff0000, v81
	v_add_f32_e32 v5, 1.0, v5
	v_rcp_f32_e32 v5, v5
	v_add_f32_e32 v37, 1.0, v37
	v_rcp_f32_e32 v38, v37
	v_mul_f32_e32 v37, 0xbfb8aa3b, v39
	v_exp_f32_e32 v37, v37
	v_mul_f32_e32 v0, 0xbfb8aa3b, v0
	v_mul_f32_e32 v1, 0xbfb8aa3b, v1
	v_exp_f32_e32 v0, v0
	v_add_f32_e32 v37, 1.0, v37
	v_rcp_f32_e32 v39, v37
	v_exp_f32_e32 v1, v1
	v_add_f32_e32 v0, 1.0, v0
	v_rcp_f32_e32 v0, v0
	v_pk_mul_f32 v[38:39], v[38:39], v[42:43]
	v_add_f32_e32 v1, 1.0, v1
	v_cvt_pk_bf16_f32 v37, v38, v39
	v_lshlrev_b32_e32 v38, 16, v82
	v_and_b32_e32 v39, 0xffff0000, v82
	v_pk_mul_f32 v[32:33], v[32:33], v[38:39]
	v_rcp_f32_e32 v1, v1
	v_cvt_pk_bf16_f32 v38, v32, v33
	v_mul_f32_e32 v32, 0xbfb8aa3b, v34
	v_mul_f32_e32 v33, 0xbfb8aa3b, v35
	v_exp_f32_e32 v32, v32
	v_exp_f32_e32 v33, v33
	v_lshlrev_b32_e32 v34, 16, v83
	v_and_b32_e32 v35, 0xffff0000, v83
	v_add_f32_e32 v32, 1.0, v32
	v_add_f32_e32 v33, 1.0, v33
	v_rcp_f32_e32 v32, v32
	v_rcp_f32_e32 v33, v33
	v_lshlrev_b64 v[102:103], 11, v[102:103]
	v_cvt_pk_bf16_f32 v55, v48, v49
; __device__ __forceinline__ unsigned cvt_pk_bf16(float lo, float hi) { const f32x2 v = {lo, hi}; return __builtin_bit_cast(unsigned, __builtin_convertvector(v, bfx2_t)); }
; __device__ __forceinline__ float bflo(unsigned w) { return __uint_as_float(w << 16); }
; __device__ __forceinline__ float bfhi(unsigned w) { return __uint_as_float(w & 0xffff0000u); }
; __device__ __forceinline__ float fsigmoid(float x) { return __builtin_amdgcn_rcpf(1.0f + __builtin_amdgcn_exp2f(-1.4426950408889634f * x)); }
;     __device__ __forceinline__ void operator()(const AccT& acc, const Unit& u, int ui, int wr, int wc, int fr, int fq) const {
;     ...
;             for (int m = 0; m < 4; ++m) {
;                 const int row = u.pm * 256 + ai * 128 + wr * 64 + m * 16 + fr;
; #pragma unroll
;                 for (int bj = 0; bj < 2; ++bj) {
;                     const int col = u.pn * 256 + bj * 128 + wc * 32 + 8 * fq;
;                     const u32x4 y = yv[m][bj];
;                     const f32x4 a0 = acc[ai][bj][m][0], a1 = acc[ai][bj][m][1];
;                     u32x4 w;
;                     w.x = cvt_pk_bf16(bflo(y.x) * fsigmoid(a0[0]), bfhi(y.x) * fsigmoid(a0[1]));
;                     w.y = cvt_pk_bf16(bflo(y.y) * fsigmoid(a0[2]), bfhi(y.y) * fsigmoid(a0[3]));
;                     w.z = cvt_pk_bf16(bflo(y.z) * fsigmoid(a1[0]), bfhi(y.z) * fsigmoid(a1[1]));
;                     w.w = cvt_pk_bf16(bflo(y.w) * fsigmoid(a1[2]), bfhi(y.w) * fsigmoid(a1[3]));
;                     *GP(u32x4, MIX + (size_t)row * DM + col) = w;
;                 }
	v_lshlrev_b64 v[48:49], 11, v[96:97]
	v_pk_mul_f32 v[32:33], v[32:33], v[34:35]
	v_lshlrev_b32_e32 v34, 16, v76
	v_and_b32_e32 v35, 0xffff0000, v76
	v_pk_mul_f32 v[28:29], v[28:29], v[34:35]
	v_lshlrev_b32_e32 v34, 16, v77
	v_cvt_pk_bf16_f32 v28, v28, v29
	v_mul_f32_e32 v29, 0xbfb8aa3b, v30
	v_exp_f32_e32 v29, v29
	v_and_b32_e32 v35, 0xffff0000, v77
	v_cvt_pk_bf16_f32 v39, v32, v33
	v_lshlrev_b64 v[32:33], 11, v[94:95]
	v_add_f32_e32 v29, 1.0, v29
	v_rcp_f32_e32 v30, v29
	v_mul_f32_e32 v29, 0xbfb8aa3b, v31
	v_exp_f32_e32 v29, v29
	v_cvt_pk_bf16_f32 v63, v56, v57
	v_lshl_add_u64 v[56:57], s[18:19], 0, v[102:103]
	v_cvt_pk_bf16_f32 v47, v40, v41
	v_add_f32_e32 v29, 1.0, v29
	v_rcp_f32_e32 v31, v29
	v_lshl_add_u64 v[40:41], s[18:19], 0, v[48:49]
	v_lshl_add_u64 v[56:57], v[56:57], 0, v[132:133]
	v_lshl_add_u64 v[40:41], v[40:41], 0, v[132:133]
	v_pk_mul_f32 v[30:31], v[30:31], v[34:35]
	global_store_dwordx4 v[56:57], v[60:63], off
	v_cvt_pk_bf16_f32 v29, v30, v31
	v_lshlrev_b32_e32 v30, 16, v78
	v_and_b32_e32 v31, 0xffff0000, v78
	v_pk_mul_f32 v[24:25], v[24:25], v[30:31]
	global_store_dwordx4 v[56:57], v[52:55], off offset:256
	v_cvt_pk_bf16_f32 v30, v24, v25
	v_mul_f32_e32 v24, 0xbfb8aa3b, v26
	v_mul_f32_e32 v25, 0xbfb8aa3b, v27
	v_exp_f32_e32 v24, v24
	v_exp_f32_e32 v25, v25
	v_lshlrev_b32_e32 v26, 16, v79
	v_and_b32_e32 v27, 0xffff0000, v79
	v_add_f32_e32 v24, 1.0, v24
	v_add_f32_e32 v25, 1.0, v25
	v_rcp_f32_e32 v24, v24
	v_rcp_f32_e32 v25, v25
	global_store_dwordx4 v[40:41], v[44:47], off
	global_store_dwordx4 v[40:41], v[36:39], off offset:256
	s_and_b64 vcc, exec, s[42:43]
	v_pk_mul_f32 v[24:25], v[24:25], v[26:27]
	v_lshlrev_b32_e32 v26, 16, v72
	v_and_b32_e32 v27, 0xffff0000, v72
	v_pk_mul_f32 v[20:21], v[20:21], v[26:27]
	v_lshlrev_b32_e32 v26, 16, v73
	v_cvt_pk_bf16_f32 v20, v20, v21
	v_mul_f32_e32 v21, 0xbfb8aa3b, v22
	v_exp_f32_e32 v21, v21
	v_and_b32_e32 v27, 0xffff0000, v73
	v_cvt_pk_bf16_f32 v31, v24, v25
	v_lshl_add_u64 v[24:25], s[18:19], 0, v[32:33]
	v_add_f32_e32 v21, 1.0, v21
	v_rcp_f32_e32 v22, v21
	v_mul_f32_e32 v21, 0xbfb8aa3b, v23
	v_exp_f32_e32 v21, v21
	v_lshl_add_u64 v[24:25], v[24:25], 0, v[132:133]
	global_store_dwordx4 v[24:25], v[28:31], off
	s_mov_b32 s77, s74
	v_add_f32_e32 v21, 1.0, v21
	v_rcp_f32_e32 v23, v21
	s_mov_b32 s76, s75
	s_mov_b64 s[16:17], s[44:45]
	s_mov_b64 s[46:47], s[0:1]
	v_pk_mul_f32 v[22:23], v[22:23], v[26:27]
	s_nop 0
	v_cvt_pk_bf16_f32 v21, v22, v23
	v_lshlrev_b32_e32 v22, 16, v74
	v_and_b32_e32 v23, 0xffff0000, v74
	v_pk_mul_f32 v[16:17], v[16:17], v[22:23]
	s_nop 0
	v_cvt_pk_bf16_f32 v22, v16, v17
	v_mul_f32_e32 v16, 0xbfb8aa3b, v18
	v_mul_f32_e32 v17, 0xbfb8aa3b, v19
	v_exp_f32_e32 v16, v16
	v_exp_f32_e32 v17, v17
	v_lshlrev_b32_e32 v18, 16, v75
	v_and_b32_e32 v19, 0xffff0000, v75
	v_add_f32_e32 v16, 1.0, v16
	v_add_f32_e32 v17, 1.0, v17
	v_rcp_f32_e32 v16, v16
	v_rcp_f32_e32 v17, v17
	s_nop 0
	v_pk_mul_f32 v[16:17], v[16:17], v[18:19]
	v_lshlrev_b32_e32 v18, 16, v68
	v_and_b32_e32 v19, 0xffff0000, v68
	v_pk_mul_f32 v[12:13], v[12:13], v[18:19]
	v_lshlrev_b32_e32 v18, 16, v69
	v_cvt_pk_bf16_f32 v12, v12, v13
	v_mul_f32_e32 v13, 0xbfb8aa3b, v14
	v_exp_f32_e32 v13, v13
	v_and_b32_e32 v19, 0xffff0000, v69
	v_cvt_pk_bf16_f32 v23, v16, v17
	v_lshlrev_b64 v[16:17], 11, v[92:93]
	v_add_f32_e32 v13, 1.0, v13
	v_rcp_f32_e32 v14, v13
	v_mul_f32_e32 v13, 0xbfb8aa3b, v15
	v_exp_f32_e32 v13, v13
	global_store_dwordx4 v[24:25], v[20:23], off offset:256
	v_add_f32_e32 v13, 1.0, v13
	v_rcp_f32_e32 v15, v13
	s_nop 0
	v_pk_mul_f32 v[14:15], v[14:15], v[18:19]
	s_nop 0
	v_cvt_pk_bf16_f32 v13, v14, v15
	v_lshlrev_b32_e32 v14, 16, v70
	v_and_b32_e32 v15, 0xffff0000, v70
	v_pk_mul_f32 v[8:9], v[8:9], v[14:15]
	s_nop 0
	v_cvt_pk_bf16_f32 v14, v8, v9
	v_mul_f32_e32 v8, 0xbfb8aa3b, v10
	v_mul_f32_e32 v9, 0xbfb8aa3b, v11
	v_exp_f32_e32 v8, v8
	v_exp_f32_e32 v9, v9
	v_lshlrev_b32_e32 v10, 16, v71
	v_and_b32_e32 v11, 0xffff0000, v71
	v_add_f32_e32 v8, 1.0, v8
	v_add_f32_e32 v9, 1.0, v9
	v_rcp_f32_e32 v8, v8
	v_rcp_f32_e32 v9, v9
	s_nop 0
	v_pk_mul_f32 v[8:9], v[8:9], v[10:11]
	v_lshlrev_b32_e32 v10, 16, v64
	v_and_b32_e32 v11, 0xffff0000, v64
	v_pk_mul_f32 v[4:5], v[4:5], v[10:11]
	v_lshlrev_b32_e32 v10, 16, v65
	v_cvt_pk_bf16_f32 v4, v4, v5
	v_mul_f32_e32 v5, 0xbfb8aa3b, v6
	v_exp_f32_e32 v5, v5
	v_and_b32_e32 v11, 0xffff0000, v65
	v_cvt_pk_bf16_f32 v15, v8, v9
	v_lshl_add_u64 v[8:9], s[18:19], 0, v[16:17]
	v_add_f32_e32 v5, 1.0, v5
	v_rcp_f32_e32 v6, v5
	v_mul_f32_e32 v5, 0xbfb8aa3b, v7
	v_exp_f32_e32 v5, v5
	v_lshl_add_u64 v[8:9], v[8:9], 0, v[132:133]
	global_store_dwordx4 v[8:9], v[12:15], off
	v_add_f32_e32 v5, 1.0, v5
	v_rcp_f32_e32 v7, v5
	s_nop 0
	v_pk_mul_f32 v[6:7], v[6:7], v[10:11]
	s_nop 0
	v_cvt_pk_bf16_f32 v5, v6, v7
	v_lshlrev_b32_e32 v6, 16, v66
	v_and_b32_e32 v7, 0xffff0000, v66
	v_pk_mul_f32 v[0:1], v[0:1], v[6:7]
	s_nop 0
	v_cvt_pk_bf16_f32 v6, v0, v1
	v_mul_f32_e32 v0, 0xbfb8aa3b, v2
	v_mul_f32_e32 v1, 0xbfb8aa3b, v3
	v_exp_f32_e32 v0, v0
	v_exp_f32_e32 v1, v1
	v_lshlrev_b32_e32 v2, 16, v67
	v_and_b32_e32 v3, 0xffff0000, v67
	v_add_f32_e32 v0, 1.0, v0
	v_add_f32_e32 v1, 1.0, v1
	v_rcp_f32_e32 v0, v0
	v_rcp_f32_e32 v1, v1
	s_nop 0
	v_pk_mul_f32 v[0:1], v[0:1], v[2:3]
	s_nop 0
	v_cvt_pk_bf16_f32 v7, v0, v1
	global_store_dwordx4 v[8:9], v[4:7], off offset:256
	s_cbranch_vccnz .LBB0_313

; __device__ __forceinline__ float bflo(unsigned w) { return __uint_as_float(w << 16); }
; __device__ __forceinline__ float bfhi(unsigned w) { return __uint_as_float(w & 0xffff0000u); }
; __device__ __forceinline__ f32x4 lo_unpack4(unsigned w) { const f32x2 a = __builtin_amdgcn_cvt_pk_f32_fp8((int)w, false), b = __builtin_amdgcn_cvt_pk_f32_fp8((int)w, true); return (f32x4){a.x, a.y, b.x, b.y} * (1.0f / 512.0f); }
; __device__ void final_norm(const Params& P, const float* ssp, const bf16_t* hi, const unsigned char* lo) {
;     ...
;     for (int row = blockIdx.x * 8 + wave; row < TT; row += G * 8) {
;         float ss = (lane < 16) ? ssp[(size_t)lane * TT + row] : 0.f;
;         u32x2 hv[4]; unsigned lv[4];
; #pragma unroll
;         for (int q = 0; q < 4; ++q) { hv[q] = *(const u32x2*)(hi + (size_t)row * DM + q * 256 + lane * 4); lv[q] = 0u; }
; #pragma unroll
;         for (int o = 32; o >= 1; o >>= 1) ss += __shfl_xor(ss, o);
;         const float r = 1.0f / sqrtf(ss * (1.0f / 1024.0f) + 1e-6f);
; #pragma unroll
;         for (int q = 0; q < 4; ++q) { const f32x4 v = (f32x4){bflo(hv[q].x), bfhi(hv[q].x), bflo(hv[q].y), bfhi(hv[q].y)} + lo_unpack4(lv[q]);
;             *(f32x4*)(out + (size_t)row * DM + q * 256 + lane * 4) = v * r * w[q]; }
;     }
.LBB0_671:
	s_or_b64 exec, exec, s[2:3]
	global_load_dwordx2 v[42:43], v[24:25], off offset:-1024 nt
	global_load_dwordx2 v[44:45], v[24:25], off offset:-512 nt
	global_load_dwordx2 v[46:47], v[24:25], off nt
	global_load_dwordx2 v[48:49], v[24:25], off offset:512 nt
	s_waitcnt vmcnt(0)
	v_mov_b32_e32 v41, v40
	s_nop 1
	v_permlane32_swap_b32_e32 v40, v41
	v_add_u32_e32 v160, v160, v164
	v_lshl_add_u64 v[20:21], v[20:21], 0, v[22:23]
	v_lshl_add_u64 v[24:25], v[24:25], 0, v[26:27]
	s_waitcnt lgkmcnt(0)
	v_add_f32_e32 v40, v40, v41
	v_mov_b32_e32 v41, v40
	s_nop 1
	v_permlane16_swap_b32_e32 v40, v41
	s_waitcnt lgkmcnt(0)
	v_add_f32_e32 v40, v40, v41
	ds_bpermute_b32 v41, v34, v40
	s_waitcnt lgkmcnt(0)
	v_add_f32_e32 v40, v40, v41
	ds_bpermute_b32 v41, v35, v40
	s_waitcnt lgkmcnt(0)
	v_add_f32_e32 v40, v40, v41
	ds_bpermute_b32 v41, v36, v40
	s_waitcnt lgkmcnt(0)
	v_add_f32_e32 v40, v40, v41
	ds_bpermute_b32 v41, v37, v40
	s_waitcnt lgkmcnt(0)
	v_add_f32_e32 v40, v40, v41
	v_fmamk_f32 v40, v40, 0x3a800000, v38
	v_mul_f32_e32 v41, 0x4f800000, v40
	v_cmp_gt_f32_e32 vcc, s6, v40
	v_lshlrev_b32_e32 v54, 16, v46
	s_nop 0
	v_cndmask_b32_e32 v40, v40, v41, vcc
	v_sqrt_f32_e32 v41, v40
	v_and_b32_e32 v55, 0xffff0000, v46
	v_lshlrev_b32_e32 v46, 16, v47
	v_and_b32_e32 v47, 0xffff0000, v47
	v_add_u32_e32 v50, -1, v41
	v_add_u32_e32 v51, 1, v41
	v_fma_f32 v52, -v50, v41, v40
	v_fma_f32 v53, -v51, v41, v40
	v_cmp_ge_f32_e64 s[2:3], 0, v52
	v_lshlrev_b32_e32 v56, 16, v48
	v_and_b32_e32 v57, 0xffff0000, v48
	v_cndmask_b32_e64 v41, v41, v50, s[2:3]
	v_cmp_lt_f32_e64 s[2:3], 0, v53
	v_lshlrev_b32_e32 v48, 16, v49
	v_and_b32_e32 v49, 0xffff0000, v49
	v_cndmask_b32_e64 v41, v41, v51, s[2:3]
	v_mul_f32_e32 v50, 0x37800000, v41
	v_cndmask_b32_e32 v41, v41, v50, vcc
	v_cmp_class_f32_e32 vcc, v40, v39
	v_pk_add_f32 v[46:47], v[16:17], v[46:47]
	v_pk_add_f32 v[54:55], v[18:19], v[54:55]
	v_cndmask_b32_e32 v40, v41, v40, vcc
	v_div_scale_f32 v41, s[2:3], v40, v40, 1.0
	v_rcp_f32_e32 v50, v41
	v_div_scale_f32 v51, vcc, 1.0, v40, 1.0
	v_pk_add_f32 v[58:59], v[16:17], v[48:49]
	v_fma_f32 v52, -v41, v50, 1.0
	v_fmac_f32_e32 v50, v52, v50
	v_mul_f32_e32 v52, v51, v50
	v_fma_f32 v53, -v41, v52, v51
	v_fmac_f32_e32 v52, v53, v50
	v_fma_f32 v41, -v41, v52, v51
	v_div_fmas_f32 v41, v41, v50, v52
	v_div_fixup_f32 v52, v41, v40, 1.0
	v_lshlrev_b32_e32 v40, 16, v42
	v_and_b32_e32 v41, 0xffff0000, v42
	v_lshlrev_b32_e32 v42, 16, v43
	v_and_b32_e32 v43, 0xffff0000, v43
	v_lshlrev_b32_e32 v50, 16, v44
	v_and_b32_e32 v51, 0xffff0000, v44
	v_lshlrev_b32_e32 v44, 16, v45
	v_and_b32_e32 v45, 0xffff0000, v45
	v_pk_add_f32 v[42:43], v[16:17], v[42:43]
	v_pk_add_f32 v[40:41], v[18:19], v[40:41]
	v_pk_add_f32 v[44:45], v[16:17], v[44:45]
	v_pk_add_f32 v[50:51], v[18:19], v[50:51]
	v_pk_mul_f32 v[40:41], v[40:41], v[52:53] op_sel_hi:[1,0]
	v_pk_mul_f32 v[42:43], v[42:43], v[52:53] op_sel_hi:[1,0]
	v_pk_mul_f32 v[48:49], v[50:51], v[52:53] op_sel_hi:[1,0]
	v_pk_mul_f32 v[44:45], v[44:45], v[52:53] op_sel_hi:[1,0]
	v_pk_mul_f32 v[54:55], v[54:55], v[52:53] op_sel_hi:[1,0]
	v_pk_mul_f32 v[50:51], v[46:47], v[52:53] op_sel_hi:[1,0]
	v_pk_mul_f32 v[42:43], v[2:3], v[42:43]
	v_pk_mul_f32 v[40:41], v[0:1], v[40:41]
	v_pk_mul_f32 v[46:47], v[6:7], v[44:45]
	v_pk_mul_f32 v[44:45], v[4:5], v[48:49]
	v_pk_mul_f32 v[50:51], v[10:11], v[50:51]
	v_pk_mul_f32 v[48:49], v[8:9], v[54:55]
	global_store_dwordx4 v[28:29], v[40:43], off offset:-3072 nt
	global_store_dwordx4 v[28:29], v[44:47], off offset:-2048 nt
	global_store_dwordx4 v[28:29], v[48:51], off offset:-1024 nt
	v_pk_add_f32 v[40:41], v[18:19], v[56:57]
	v_pk_mul_f32 v[42:43], v[58:59], v[52:53] op_sel_hi:[1,0]
	v_pk_mul_f32 v[40:41], v[40:41], v[52:53] op_sel_hi:[1,0]
	v_pk_mul_f32 v[42:43], v[14:15], v[42:43]
	v_pk_mul_f32 v[40:41], v[12:13], v[40:41]
	v_cmp_lt_i32_e32 vcc, s7, v160
	global_store_dwordx4 v[28:29], v[40:43], off nt
	s_or_b64 s[4:5], vcc, s[4:5]
	v_lshl_add_u64 v[28:29], v[28:29], 0, v[30:31]
	s_andn2_b64 exec, exec, s[4:5]
	s_cbranch_execz .LBB0_674
